# gMLP spatial weights prefetched once per item (k-loops unrolled, counted vmcnt) on top of hand-scheduled FoX band steps
# baseline (speedup 1.0000x reference)
.LBB0_545:
	s_or_b64 exec, exec, s[34:35]
	s_or_b32 s2, s14, s10
	s_lshl_b32 s80, s2, 7
	v_lshl_add_u64 v[12:13], s[80:81], 2, v[22:23]
	v_lshlrev_b32_e32 v22, 16, v109
	v_mov_b32_e32 v33, v191
	v_lshl_add_u64 v[20:21], s[24:25], 0, v[32:33]
	v_or_b32_e32 v190, 32, v32
	s_add_i32 s13, s13, s72
	s_sub_i32 s12, s12, s72
	s_cmpk_gt_i32 s13, 0x1ff
	v_mov_b32_e32 v12, v246
	v_mov_b32_e32 v13, v247
	v_mov_b32_e32 v14, v248
	v_mov_b32_e32 v15, v249
	v_add_f32_e32 v16, v16, v12
	v_mul_f32_e32 v16, v16, v22
	v_lshlrev_b32_e32 v22, 16, v108
	v_mul_f32_e32 v16, v16, v22
	v_lshlrev_b64 v[22:23], 11, v[34:35]
	v_cvt_pk_bf16_f32 v16, v16, s0
	v_lshl_add_u64 v[24:25], v[20:21], 0, v[22:23]
	global_store_short v[24:25], v16, off
	v_add_f32_e32 v16, v17, v13
	v_lshlrev_b32_e32 v17, 16, v107
	v_mul_f32_e32 v16, v16, v17
	v_lshlrev_b32_e32 v17, 16, v106
	v_mul_f32_e32 v16, v16, v17
	v_or_b32_e32 v24, 0x800, v22
	v_mov_b32_e32 v25, v23
	v_cvt_pk_bf16_f32 v26, v16, s0
	v_lshl_add_u64 v[16:17], v[20:21], 0, v[24:25]
	global_store_short v[16:17], v26, off
	v_add_f32_e32 v16, v18, v14
	v_lshlrev_b32_e32 v17, 16, v105
	v_mul_f32_e32 v16, v16, v17
	v_lshlrev_b32_e32 v17, 16, v104
	v_mul_f32_e32 v16, v16, v17
	v_or_b32_e32 v26, 0x1000, v22
	v_mov_b32_e32 v27, v23
	v_cvt_pk_bf16_f32 v18, v16, s0
	v_lshl_add_u64 v[16:17], v[20:21], 0, v[26:27]
	global_store_short v[16:17], v18, off
	v_add_f32_e32 v16, v19, v15
	v_lshlrev_b32_e32 v17, 16, v103
	v_mul_f32_e32 v16, v16, v17
	v_lshlrev_b32_e32 v17, 16, v102
	v_mul_f32_e32 v16, v16, v17
	v_or_b32_e32 v28, 0x1800, v22
	v_mov_b32_e32 v29, v23
	v_cvt_pk_bf16_f32 v18, v16, s0
	v_lshl_add_u64 v[16:17], v[20:21], 0, v[28:29]
	global_store_short v[16:17], v18, off
	v_add_f32_e32 v8, v8, v12
	v_lshlrev_b32_e32 v16, 16, v101
	v_mul_f32_e32 v8, v8, v16
	v_lshlrev_b32_e32 v16, 16, v100
	v_mul_f32_e32 v8, v8, v16
	v_lshl_add_u64 v[16:17], s[24:25], 0, v[22:23]
	v_cvt_pk_bf16_f32 v8, v8, s0
	v_lshl_add_u64 v[18:19], v[16:17], 0, v[190:191]
	global_store_short v[18:19], v8, off
	v_add_f32_e32 v8, v9, v13
	v_lshlrev_b32_e32 v9, 16, v99
	v_mul_f32_e32 v8, v8, v9
	v_lshlrev_b32_e32 v9, 16, v98
	v_mul_f32_e32 v8, v8, v9
	v_cvt_pk_bf16_f32 v20, v8, s0
	v_lshl_add_u64 v[8:9], s[24:25], 0, v[24:25]
	v_lshl_add_u64 v[18:19], v[8:9], 0, v[190:191]
	global_store_short v[18:19], v20, off
	v_add_f32_e32 v10, v10, v14
	v_lshlrev_b32_e32 v18, 16, v97
	v_mul_f32_e32 v10, v10, v18
	v_lshlrev_b32_e32 v18, 16, v96
	v_mul_f32_e32 v10, v10, v18
	v_lshl_add_u64 v[18:19], s[24:25], 0, v[26:27]
	v_cvt_pk_bf16_f32 v10, v10, s0
	v_lshl_add_u64 v[20:21], v[18:19], 0, v[190:191]
	global_store_short v[20:21], v10, off
	v_add_f32_e32 v10, v11, v15
	v_lshlrev_b32_e32 v11, 16, v95
	v_mul_f32_e32 v10, v10, v11
	v_lshlrev_b32_e32 v11, 16, v94
	v_mul_f32_e32 v10, v10, v11
	v_cvt_pk_bf16_f32 v22, v10, s0
	v_lshl_add_u64 v[10:11], s[24:25], 0, v[28:29]
	v_lshl_add_u64 v[20:21], v[10:11], 0, v[190:191]
	global_store_short v[20:21], v22, off
	v_add_f32_e32 v4, v4, v12
	v_lshlrev_b32_e32 v20, 16, v93
	v_mul_f32_e32 v4, v4, v20
	v_lshlrev_b32_e32 v20, 16, v92
	v_mul_f32_e32 v4, v4, v20
	v_or_b32_e32 v190, 64, v32
	v_cvt_pk_bf16_f32 v4, v4, s0
	v_lshl_add_u64 v[20:21], v[16:17], 0, v[190:191]
	global_store_short v[20:21], v4, off
	v_add_f32_e32 v4, v5, v13
	v_lshlrev_b32_e32 v5, 16, v88
	v_mul_f32_e32 v4, v4, v5
	v_lshlrev_b32_e32 v5, 16, v87
	v_mul_f32_e32 v4, v4, v5
	v_cvt_pk_bf16_f32 v20, v4, s0
	v_lshl_add_u64 v[4:5], v[8:9], 0, v[190:191]
	global_store_short v[4:5], v20, off
	v_add_f32_e32 v4, v6, v14
	v_lshlrev_b32_e32 v5, 16, v85
	v_mul_f32_e32 v4, v4, v5
	v_lshlrev_b32_e32 v5, 16, v84
	v_mul_f32_e32 v4, v4, v5
	v_cvt_pk_bf16_f32 v6, v4, s0
	v_lshl_add_u64 v[4:5], v[18:19], 0, v[190:191]
	global_store_short v[4:5], v6, off
	v_add_f32_e32 v4, v7, v15
	v_lshlrev_b32_e32 v5, 16, v83
	v_mul_f32_e32 v4, v4, v5
	v_lshlrev_b32_e32 v5, 16, v82
	v_mul_f32_e32 v4, v4, v5
	v_cvt_pk_bf16_f32 v6, v4, s0
	v_lshl_add_u64 v[4:5], v[10:11], 0, v[190:191]
	global_store_short v[4:5], v6, off
	v_add_f32_e32 v0, v0, v12
	v_lshlrev_b32_e32 v4, 16, v41
	v_mul_f32_e32 v0, v0, v4
	v_lshlrev_b32_e32 v4, 16, v89
	v_mul_f32_e32 v0, v0, v4
	v_or_b32_e32 v190, 0x60, v32
	v_cvt_pk_bf16_f32 v0, v0, s0
	v_lshl_add_u64 v[4:5], v[16:17], 0, v[190:191]
	global_store_short v[4:5], v0, off
	v_add_f32_e32 v0, v1, v13
	v_lshlrev_b32_e32 v1, 16, v86
	v_mul_f32_e32 v0, v0, v1
	v_lshlrev_b32_e32 v1, 16, v91
	v_mul_f32_e32 v0, v0, v1
	v_cvt_pk_bf16_f32 v4, v0, s0
	v_lshl_add_u64 v[0:1], v[8:9], 0, v[190:191]
	global_store_short v[0:1], v4, off
	v_add_f32_e32 v0, v2, v14
	v_lshlrev_b32_e32 v1, 16, v90
	v_mul_f32_e32 v0, v0, v1
	v_lshlrev_b32_e32 v1, 16, v71
	v_mul_f32_e32 v0, v0, v1
	v_cvt_pk_bf16_f32 v2, v0, s0
	v_lshl_add_u64 v[0:1], v[18:19], 0, v[190:191]
	global_store_short v[0:1], v2, off
	v_add_f32_e32 v0, v3, v15
	v_lshlrev_b32_e32 v1, 16, v70
	v_mul_f32_e32 v0, v0, v1
	v_lshlrev_b32_e32 v1, 16, v68
	v_mul_f32_e32 v0, v0, v1
	v_cvt_pk_bf16_f32 v2, v0, s0
	v_lshl_add_u64 v[0:1], v[10:11], 0, v[190:191]
	global_store_short v[0:1], v2, off
	s_barrier
	s_cbranch_scc1 .LBB0_554
.LBB0_546:
	s_add_i32 s2, s13, s60
	s_cmpk_lt_i32 s2, 0x200
	s_cselect_b32 s2, s2, -1
	s_cmp_lt_i32 s2, 0
	s_cselect_b32 s2, s13, s2
	s_ashr_i32 s20, s13, 7
	v_mov_b32_e32 v143, v184
	s_ashr_i32 s21, s20, 31
	s_lshl_b32 s3, s13, 5
	s_lshl_b64 s[20:21], s[20:21], 12
	v_ashrrev_i32_e32 v40, 2, v143
	s_and_b32 s3, s3, 0xf80
	v_ashrrev_i32_e32 v41, 31, v40
	v_lshlrev_b32_e32 v0, 4, v143
	s_or_b32 s20, s20, s3
	v_and_b32_e32 v146, 48, v0
	v_lshl_add_u64 v[0:1], s[20:21], 0, v[40:41]
	v_mov_b64_e32 v[16:17], s[26:27]
	v_mad_u64_u32 v[2:3], s[34:35], v0, s70, v[16:17]
	s_and_b32 s15, s13, 3
	s_ashr_i32 s34, s2, 7
	v_mad_i32_i24 v3, v1, s70, v3
	s_lshl_b32 s80, s15, 7
	s_and_b32 s14, s2, 3
	s_ashr_i32 s35, s34, 31
	s_lshl_b32 s2, s2, 5
	v_lshl_add_u64 v[0:1], v[2:3], 0, s[80:81]
	v_lshlrev_b32_e32 v190, 1, v146
	s_lshl_b64 s[34:35], s[34:35], 12
	s_and_b32 s2, s2, 0xf80
	v_lshl_add_u64 v[4:5], v[0:1], 0, v[190:191]
	s_or_b32 s34, s34, s2
	global_load_dwordx4 v[0:3], v[4:5], off offset:512
	global_load_dwordx4 v[12:15], v[4:5], off offset:528
	v_lshl_add_u64 v[4:5], s[34:35], 0, v[40:41]
	v_mad_u64_u32 v[6:7], s[36:37], v4, s70, v[16:17]
	v_mad_i32_i24 v7, v5, s70, v7
	s_lshl_b32 s80, s14, 7
	v_lshl_add_u64 v[4:5], v[6:7], 0, s[80:81]
	v_lshl_add_u64 v[8:9], v[4:5], 0, v[190:191]
	global_load_dwordx4 v[4:7], v[8:9], off offset:512
	s_nop 0
	global_load_dwordx4 v[8:11], v[8:9], off offset:528
	v_bfe_u32 v145, v143, 4, 2
	v_and_b32_e32 v38, -16, v40
	v_ashrrev_i32_e32 v39, 31, v38
	v_lshlrev_b32_e32 v142, 2, v145
	v_or_b32_e32 v18, v38, v142
	v_mov_b32_e32 v19, v39
	v_and_b32_e32 v144, 15, v143
	v_lshl_add_u64 v[36:37], v[18:19], 0, s[20:21]
	v_lshl_or_b32 v22, s15, 6, v144
	v_mad_u64_u32 v[20:21], s[20:21], v36, s70, v[16:17]
	v_mad_i32_i24 v21, v37, s70, v21
	v_lshlrev_b32_e32 v190, 1, v22
	v_lshl_add_u64 v[20:21], v[20:21], 0, v[190:191]
	v_add_co_u32_e32 v24, vcc, s76, v20
	s_movk_i32 s2, 0x5000
	s_nop 0
	v_addc_co_u32_e32 v25, vcc, 0, v21, vcc
	v_add_co_u32_e32 v26, vcc, s73, v20
	s_mov_b64 s[36:37], 0x1e00
	s_nop 0
	v_addc_co_u32_e32 v27, vcc, 0, v21, vcc
	s_mov_b64 s[40:41], 0x3c00
	v_add_co_u32_e32 v28, vcc, s2, v20
	global_load_ushort v141, v[20:21], off
	global_load_ushort v140, v[20:21], off offset:1024
	v_lshl_add_u64 v[22:23], v[20:21], 0, s[36:37]
	global_load_ushort v139, v[24:25], off offset:3584
	global_load_ushort v138, v[22:23], off offset:1024
	v_lshl_add_u64 v[24:25], v[20:21], 0, s[40:41]
	s_mov_b64 s[42:43], 0x5a00
	v_addc_co_u32_e32 v29, vcc, 0, v21, vcc
	global_load_ushort v137, v[26:27], off offset:3072
	global_load_ushort v136, v[24:25], off offset:1024
	v_lshl_add_u64 v[26:27], v[20:21], 0, s[42:43]
	global_load_ushort v135, v[28:29], off offset:2560
	global_load_ushort v134, v[26:27], off offset:1024
	global_load_ushort v133, v[20:21], off offset:32
	global_load_ushort v132, v[20:21], off offset:1056
	global_load_ushort v131, v[22:23], off offset:32
	global_load_ushort v130, v[22:23], off offset:1056
	global_load_ushort v129, v[24:25], off offset:32
	global_load_ushort v128, v[24:25], off offset:1056
	global_load_ushort v127, v[26:27], off offset:32
	global_load_ushort v126, v[26:27], off offset:1056
	global_load_ushort v120, v[20:21], off offset:64
	global_load_ushort v119, v[20:21], off offset:1088
	global_load_ushort v117, v[22:23], off offset:64
	global_load_ushort v116, v[22:23], off offset:1088
	global_load_ushort v114, v[24:25], off offset:64
	global_load_ushort v113, v[24:25], off offset:1088
	global_load_ushort v112, v[26:27], off offset:64
	global_load_ushort v111, v[26:27], off offset:1088
	global_load_ushort v110, v[20:21], off offset:96
	global_load_ushort v118, v[20:21], off offset:1120
	global_load_ushort v115, v[22:23], off offset:96
	global_load_ushort v122, v[22:23], off offset:1120
	global_load_ushort v121, v[24:25], off offset:96
	global_load_ushort v124, v[24:25], off offset:1120
	global_load_ushort v123, v[26:27], off offset:96
	global_load_ushort v125, v[26:27], off offset:1120
	v_lshl_add_u64 v[34:35], v[18:19], 0, s[34:35]
	v_lshl_or_b32 v18, s14, 6, v144
	v_mad_u64_u32 v[16:17], s[20:21], v34, s70, v[16:17]
	v_mad_i32_i24 v17, v35, s70, v17
	v_lshlrev_b32_e32 v32, 1, v18
	v_mov_b32_e32 v33, v191
	v_lshl_add_u64 v[16:17], v[16:17], 0, v[32:33]
	v_add_co_u32_e32 v20, vcc, s76, v16
	global_load_ushort v109, v[16:17], off
	global_load_ushort v108, v[16:17], off offset:1024
	v_addc_co_u32_e32 v21, vcc, 0, v17, vcc
	v_lshl_add_u64 v[18:19], v[16:17], 0, s[36:37]
	global_load_ushort v107, v[20:21], off offset:3584
	global_load_ushort v106, v[18:19], off offset:1024
	v_add_co_u32_e32 v20, vcc, s73, v16
	v_lshl_add_u64 v[70:71], v[16:17], 0, s[40:41]
	s_nop 0
	v_addc_co_u32_e32 v21, vcc, 0, v17, vcc
	global_load_ushort v105, v[20:21], off offset:3072
	global_load_ushort v104, v[70:71], off offset:1024
	v_add_co_u32_e32 v20, vcc, s2, v16
	v_lshl_add_u64 v[68:69], v[16:17], 0, s[42:43]
	s_nop 0
	v_addc_co_u32_e32 v21, vcc, 0, v17, vcc
	global_load_ushort v103, v[20:21], off offset:2560
	global_load_ushort v102, v[68:69], off offset:1024
	global_load_ushort v101, v[16:17], off offset:32
	global_load_ushort v100, v[16:17], off offset:1056
	global_load_ushort v99, v[18:19], off offset:32
	global_load_ushort v98, v[18:19], off offset:1056
	global_load_ushort v97, v[70:71], off offset:32
	global_load_ushort v96, v[70:71], off offset:1056
	global_load_ushort v95, v[68:69], off offset:32
	global_load_ushort v94, v[68:69], off offset:1056
	global_load_ushort v93, v[16:17], off offset:64
	global_load_ushort v92, v[16:17], off offset:1088
	global_load_ushort v88, v[18:19], off offset:64
	global_load_ushort v87, v[18:19], off offset:1088
	global_load_ushort v85, v[70:71], off offset:64
	global_load_ushort v84, v[70:71], off offset:1088
	global_load_ushort v83, v[68:69], off offset:64
	global_load_ushort v82, v[68:69], off offset:1088
	global_load_ushort v41, v[16:17], off offset:96
	global_load_ushort v89, v[16:17], off offset:1120
	global_load_ushort v86, v[18:19], off offset:96
	global_load_ushort v91, v[18:19], off offset:1120
	global_load_ushort v90, v[70:71], off offset:96
	v_and_b32_e32 v17, 64, v227
	v_xor_b32_e32 v16, 1, v227
	v_add_u32_e32 v17, 64, v17
	v_cmp_lt_i32_e32 vcc, v16, v17
	s_lshl_b32 s34, s15, 8
	s_mov_b32 s35, s81
	s_waitcnt vmcnt(62)
	v_lshlrev_b32_e32 v25, 16, v0
	v_and_b32_e32 v27, 0xffff0000, v0
	v_lshlrev_b32_e32 v51, 16, v1
	v_and_b32_e32 v53, 0xffff0000, v1
	v_lshlrev_b32_e32 v55, 16, v2
	v_and_b32_e32 v153, 0xffff0000, v2
	v_lshlrev_b32_e32 v155, 16, v3
	v_lshlrev_b32_e32 v45, 16, v12
	v_lshlrev_b32_e32 v24, 16, v4
	v_and_b32_e32 v26, 0xffff0000, v4
	v_pk_add_f32 v[0:1], v[24:25], 0 op_sel_hi:[1,0]
	v_lshlrev_b32_e32 v50, 16, v5
	v_pk_add_f32 v[0:1], v[0:1], v[26:27]
	v_and_b32_e32 v52, 0xffff0000, v5
	v_pk_add_f32 v[0:1], v[0:1], v[50:51]
	v_lshlrev_b32_e32 v54, 16, v6
	v_pk_add_f32 v[0:1], v[0:1], v[52:53]
	v_and_b32_e32 v152, 0xffff0000, v6
	v_pk_add_f32 v[0:1], v[0:1], v[54:55]
	v_lshlrev_b32_e32 v154, 16, v7
	v_pk_add_f32 v[0:1], v[0:1], v[152:153]
	s_waitcnt vmcnt(61)
	v_lshlrev_b32_e32 v49, 16, v8
	v_and_b32_e32 v157, 0xffff0000, v3
	v_and_b32_e32 v156, 0xffff0000, v7
	v_pk_add_f32 v[0:1], v[0:1], v[154:155]
	v_and_b32_e32 v44, 0xffff0000, v12
	v_and_b32_e32 v48, 0xffff0000, v8
	v_pk_add_f32 v[0:1], v[0:1], v[156:157]
	v_mov_b32_e32 v2, v49
	v_mov_b32_e32 v3, v45
	v_lshlrev_b32_e32 v43, 16, v13
	v_lshlrev_b32_e32 v47, 16, v9
	v_pk_add_f32 v[0:1], v[0:1], v[2:3]
	v_mov_b32_e32 v2, v48
	v_mov_b32_e32 v3, v44
	v_and_b32_e32 v42, 0xffff0000, v13
	v_and_b32_e32 v46, 0xffff0000, v9
	v_pk_add_f32 v[0:1], v[0:1], v[2:3]
	v_mov_b32_e32 v2, v47
	v_mov_b32_e32 v3, v43
	v_lshlrev_b32_e32 v31, 16, v14
	v_lshlrev_b32_e32 v151, 16, v10
	v_pk_add_f32 v[0:1], v[0:1], v[2:3]
	v_mov_b32_e32 v2, v46
	v_mov_b32_e32 v3, v42
	v_and_b32_e32 v30, 0xffff0000, v14
	v_and_b32_e32 v150, 0xffff0000, v10
	v_pk_add_f32 v[0:1], v[0:1], v[2:3]
	v_mov_b32_e32 v2, v151
	v_mov_b32_e32 v3, v31
	v_lshlrev_b32_e32 v29, 16, v15
	v_lshlrev_b32_e32 v149, 16, v11
	v_pk_add_f32 v[0:1], v[0:1], v[2:3]
	v_mov_b32_e32 v2, v150
	v_mov_b32_e32 v3, v30
	v_and_b32_e32 v28, 0xffff0000, v15
	v_and_b32_e32 v148, 0xffff0000, v11
	v_pk_add_f32 v[0:1], v[0:1], v[2:3]
	v_mov_b32_e32 v2, v149
	v_mov_b32_e32 v3, v29
	v_cndmask_b32_e32 v16, v227, v16, vcc
	v_pk_add_f32 v[0:1], v[0:1], v[2:3]
	v_mov_b32_e32 v2, v148
	v_mov_b32_e32 v3, v28
	v_lshlrev_b32_e32 v33, 2, v16
	v_xor_b32_e32 v16, 2, v227
	v_pk_add_f32 v[4:5], v[0:1], v[2:3]
	v_cmp_lt_i32_e32 vcc, v16, v17
	ds_bpermute_b32 v7, v33, v5
	ds_bpermute_b32 v6, v33, v4
	v_cndmask_b32_e32 v16, v227, v16, vcc
	v_lshlrev_b32_e32 v147, 2, v16
	v_lshlrev_b32_e32 v16, 2, v146
	v_mov_b32_e32 v17, v191
	v_lshl_add_u64 v[64:65], s[18:19], 0, v[16:17]
	v_lshl_add_u64 v[66:67], s[28:29], 0, v[16:17]
	v_lshl_add_u64 v[158:159], v[64:65], 0, s[34:35]
	v_lshl_add_u64 v[160:161], v[66:67], 0, s[34:35]
	global_load_dwordx4 v[0:3], v[158:159], off offset:32
	global_load_dwordx4 v[8:11], v[158:159], off offset:16
	s_waitcnt lgkmcnt(0)
	v_pk_add_f32 v[56:57], v[4:5], v[6:7]
	global_load_dwordx4 v[16:19], v[158:159], off
	global_load_dwordx4 v[4:7], v[160:161], off offset:32
	global_load_dwordx4 v[12:15], v[160:161], off offset:16
	global_load_dwordx4 v[20:23], v[160:161], off
	ds_bpermute_b32 v59, v147, v57
	ds_bpermute_b32 v58, v147, v56
	s_lshl_b32 s20, s14, 8
	s_mov_b32 s21, s81
	s_waitcnt lgkmcnt(0)
	v_pk_add_f32 v[162:163], v[56:57], v[58:59]
	s_nop 0
	v_pk_fma_f32 v[62:63], v[162:163], s[8:9], v[26:27] op_sel_hi:[1,0,1] neg_lo:[1,0,0] neg_hi:[1,0,0]
	v_pk_fma_f32 v[72:73], v[162:163], s[8:9], v[24:25] op_sel_hi:[1,0,1] neg_lo:[1,0,0] neg_hi:[1,0,0]
	v_pk_mul_f32 v[24:25], v[62:63], v[62:63]
	v_pk_fma_f32 v[60:61], v[162:163], s[8:9], v[50:51] op_sel_hi:[1,0,1] neg_lo:[1,0,0] neg_hi:[1,0,0]
	v_pk_fma_f32 v[24:25], v[72:73], v[72:73], v[24:25]
	v_pk_fma_f32 v[58:59], v[162:163], s[8:9], v[52:53] op_sel_hi:[1,0,1] neg_lo:[1,0,0] neg_hi:[1,0,0]
	v_pk_fma_f32 v[24:25], v[60:61], v[60:61], v[24:25]
	v_pk_fma_f32 v[56:57], v[162:163], s[8:9], v[54:55] op_sel_hi:[1,0,1] neg_lo:[1,0,0] neg_hi:[1,0,0]
	v_pk_fma_f32 v[24:25], v[58:59], v[58:59], v[24:25]
	v_pk_mul_f32 v[164:165], v[162:163], s[8:9] op_sel_hi:[1,0]
	v_pk_fma_f32 v[24:25], v[56:57], v[56:57], v[24:25]
	v_pk_fma_f32 v[54:55], v[162:163], s[8:9], v[152:153] op_sel_hi:[1,0,1] neg_lo:[1,0,0] neg_hi:[1,0,0]
	v_pk_add_f32 v[80:81], v[44:45], v[164:165] op_sel:[0,1] neg_lo:[0,1] neg_hi:[0,1]
	v_pk_fma_f32 v[24:25], v[54:55], v[54:55], v[24:25]
	v_pk_fma_f32 v[52:53], v[162:163], s[8:9], v[154:155] op_sel_hi:[1,0,1] neg_lo:[1,0,0] neg_hi:[1,0,0]
	v_pk_add_f32 v[48:49], v[48:49], v[164:165] op_sel_hi:[1,0] neg_lo:[0,1] neg_hi:[0,1]
	v_pk_mul_f32 v[166:167], v[80:81], v[80:81]
	v_pk_fma_f32 v[24:25], v[52:53], v[52:53], v[24:25]
	v_pk_fma_f32 v[50:51], v[162:163], s[8:9], v[156:157] op_sel_hi:[1,0,1] neg_lo:[1,0,0] neg_hi:[1,0,0]
	v_pk_mul_f32 v[26:27], v[48:49], v[48:49]
	v_pk_add_f32 v[78:79], v[42:43], v[164:165] op_sel:[0,1] neg_lo:[0,1] neg_hi:[0,1]
	v_pk_fma_f32 v[24:25], v[50:51], v[50:51], v[24:25]
	v_mov_b32_e32 v42, v27
	v_mov_b32_e32 v43, v167
	v_pk_add_f32 v[46:47], v[46:47], v[164:165] op_sel_hi:[1,0] neg_lo:[0,1] neg_hi:[0,1]
	v_pk_mul_f32 v[168:169], v[78:79], v[78:79]
	v_pk_add_f32 v[24:25], v[42:43], v[24:25]
	v_pk_mul_f32 v[152:153], v[46:47], v[46:47]
	v_mov_b32_e32 v27, v166
	v_pk_add_f32 v[76:77], v[30:31], v[164:165] op_sel:[0,1] neg_lo:[0,1] neg_hi:[0,1]
	v_pk_add_f32 v[44:45], v[150:151], v[164:165] op_sel_hi:[1,0] neg_lo:[0,1] neg_hi:[0,1]
	v_pk_add_f32 v[24:25], v[26:27], v[24:25]
	v_mov_b32_e32 v26, v153
	v_mov_b32_e32 v27, v169
	v_pk_mul_f32 v[30:31], v[76:77], v[76:77]
	v_pk_mul_f32 v[150:151], v[44:45], v[44:45]
	v_pk_add_f32 v[24:25], v[26:27], v[24:25]
	v_mov_b32_e32 v153, v168
	v_pk_add_f32 v[74:75], v[28:29], v[164:165] op_sel:[0,1] neg_lo:[0,1] neg_hi:[0,1]
	v_pk_add_f32 v[42:43], v[148:149], v[164:165] op_sel_hi:[1,0] neg_lo:[0,1] neg_hi:[0,1]
	v_pk_add_f32 v[24:25], v[152:153], v[24:25]
	v_mov_b32_e32 v26, v151
	v_mov_b32_e32 v27, v31
	v_pk_mul_f32 v[28:29], v[74:75], v[74:75]
	v_pk_mul_f32 v[148:149], v[42:43], v[42:43]
	v_pk_add_f32 v[24:25], v[26:27], v[24:25]
	v_mov_b32_e32 v151, v30
	v_pk_add_f32 v[24:25], v[150:151], v[24:25]
	v_mov_b32_e32 v26, v149
	v_mov_b32_e32 v27, v29
	v_pk_add_f32 v[24:25], v[26:27], v[24:25]
	v_mov_b32_e32 v149, v28
	v_pk_add_f32 v[148:149], v[148:149], v[24:25]
	ds_bpermute_b32 v151, v33, v149
	ds_bpermute_b32 v150, v33, v148
	global_load_dwordx4 v[24:27], v[158:159], off offset:48
	global_load_dwordx4 v[28:31], v[160:161], off offset:48
	s_nop 0
	global_load_ushort v71, v[70:71], off offset:1120
	s_nop 0
	global_load_ushort v70, v[68:69], off offset:96
	v_lshlrev_b32_e32 v33, 1, v40
	global_load_ushort v68, v[68:69], off offset:1120
	v_mul_u32_u24_e32 v69, 0x110, v146
	s_waitcnt lgkmcnt(0)
	v_pk_add_f32 v[148:149], v[148:149], v[150:151]
	ds_bpermute_b32 v151, v147, v149
	ds_bpermute_b32 v150, v147, v148
	v_add3_u32 v33, 0, v33, v69
	v_lshl_add_u64 v[160:161], v[64:65], 0, s[20:21]
	v_lshl_add_u64 v[162:163], v[66:67], 0, s[20:21]
	s_waitcnt lgkmcnt(0)
	v_pk_add_f32 v[146:147], v[148:149], v[150:151]
	s_nop 0
	v_pk_fma_f32 v[158:159], v[146:147], s[8:9], v[192:193] op_sel_hi:[1,0,0]
	global_load_dwordx4 v[64:67], v[160:161], off
	global_load_dwordx4 v[146:149], v[162:163], off
	v_mul_f32_e32 v69, 0x4b800000, v159
	v_cmp_gt_f32_e32 vcc, s93, v159
	v_cmp_gt_f32_e64 s[40:41], s93, v158
	s_nop 0
	v_cndmask_b32_e32 v69, v159, v69, vcc
	v_rsq_f32_e32 v69, v69
	s_nop 0
	v_mul_f32_e32 v150, 0x45800000, v69
	v_cndmask_b32_e32 v69, v69, v150, vcc
	v_mul_f32_e32 v73, v73, v69
	s_waitcnt vmcnt(7)
	v_fma_f32 v16, v16, v73, v20
	v_cvt_pk_bf16_f32 v16, v16, s0
	ds_write_b16 v33, v16
	v_mul_f32_e32 v16, v63, v69
	v_fma_f32 v16, v17, v16, v21
	v_cvt_pk_bf16_f32 v16, v16, s0
	ds_write_b16 v33, v16 offset:272
	v_mul_f32_e32 v16, v61, v69
	v_fma_f32 v16, v18, v16, v22
	global_load_dwordx4 v[150:153], v[160:161], off offset:16
	global_load_dwordx4 v[154:157], v[162:163], off offset:16
	v_cvt_pk_bf16_f32 v16, v16, s0
	ds_write_b16 v33, v16 offset:544
	v_mul_f32_e32 v16, v59, v69
	v_fmac_f32_e32 v23, v19, v16
	v_cvt_pk_bf16_f32 v16, v23, s0
	ds_write_b16 v33, v16 offset:816
	v_mul_f32_e32 v16, v57, v69
	v_fma_f32 v8, v8, v16, v12
	v_cvt_pk_bf16_f32 v8, v8, s0
	ds_write_b16 v33, v8 offset:1088
	v_mul_f32_e32 v8, v55, v69
	v_fma_f32 v8, v9, v8, v13
	v_cvt_pk_bf16_f32 v8, v8, s0
	ds_write_b16 v33, v8 offset:1360
	global_load_dwordx4 v[16:19], v[160:161], off offset:32
	global_load_dwordx4 v[20:23], v[162:163], off offset:32
	v_mul_f32_e32 v8, v53, v69
	v_fma_f32 v8, v10, v8, v14
	v_cvt_pk_bf16_f32 v8, v8, s0
	ds_write_b16 v33, v8 offset:1632
	v_mul_f32_e32 v8, v51, v69
	v_fmac_f32_e32 v15, v11, v8
	v_cvt_pk_bf16_f32 v8, v15, s0
	ds_write_b16 v33, v8 offset:1904
	v_mul_f32_e32 v8, v81, v69
	v_fma_f32 v0, v0, v8, v4
	v_cvt_pk_bf16_f32 v0, v0, s0
	ds_write_b16 v33, v0 offset:2176
	global_load_dwordx4 v[8:11], v[160:161], off offset:48
	global_load_dwordx4 v[12:15], v[162:163], off offset:48
	v_mul_f32_e32 v0, v80, v69
	v_fma_f32 v0, v0, v1, v5
	v_cvt_pk_bf16_f32 v0, v0, s0
	ds_write_b16 v33, v0 offset:2448
	v_mul_f32_e32 v0, v79, v69
	v_fma_f32 v0, v0, v2, v6
	v_cvt_pk_bf16_f32 v0, v0, s0
	ds_write_b16 v33, v0 offset:2720
	v_mul_f32_e32 v0, v78, v69
	v_fmac_f32_e32 v7, v0, v3
	v_cvt_pk_bf16_f32 v0, v7, s0
	ds_write_b16 v33, v0 offset:2992
	v_mul_f32_e32 v0, v77, v69
	v_mul_f32_e32 v1, 0x4b800000, v158
	s_waitcnt vmcnt(11)
	v_fma_f32 v0, v0, v24, v28
	v_cvt_pk_bf16_f32 v0, v0, s0
	ds_write_b16 v33, v0 offset:3264
	v_mul_f32_e32 v0, v76, v69
	v_fma_f32 v0, v0, v25, v29
	v_cvt_pk_bf16_f32 v0, v0, s0
	ds_write_b16 v33, v0 offset:3536
	v_mul_f32_e32 v0, v75, v69
	v_fma_f32 v0, v0, v26, v30
	v_cndmask_b32_e64 v1, v158, v1, s[40:41]
	v_cvt_pk_bf16_f32 v0, v0, s0
	v_rsq_f32_e32 v1, v1
	ds_write_b16 v33, v0 offset:3808
	v_mul_f32_e32 v0, v74, v69
	v_fmac_f32_e32 v31, v0, v27
	v_cvt_pk_bf16_f32 v0, v31, s0
	ds_write_b16 v33, v0 offset:4080
	v_mul_f32_e32 v0, 0x45800000, v1
	v_cndmask_b32_e64 v0, v1, v0, s[40:41]
	v_mul_f32_e32 v1, v72, v0
	s_waitcnt vmcnt(6)
	v_fma_f32 v1, v64, v1, v146
	v_cvt_pk_bf16_f32 v1, v1, s0
	ds_write_b16 v33, v1 offset:17408
	v_mul_f32_e32 v1, v62, v0
	v_fma_f32 v1, v65, v1, v147
	v_cvt_pk_bf16_f32 v1, v1, s0
	ds_write_b16 v33, v1 offset:17680
	v_mul_f32_e32 v1, v60, v0
	v_fma_f32 v1, v66, v1, v148
	v_cvt_pk_bf16_f32 v1, v1, s0
	ds_write_b16 v33, v1 offset:17952
	v_mul_f32_e32 v1, v58, v0
	v_fmac_f32_e32 v149, v67, v1
	v_cvt_pk_bf16_f32 v1, v149, s0
	ds_write_b16 v33, v1 offset:18224
	v_mul_f32_e32 v1, v56, v0
	v_bfi_b32 v24, -16, v40, v143
	s_waitcnt vmcnt(4)
	v_fma_f32 v1, v150, v1, v154
	v_cvt_pk_bf16_f32 v1, v1, s0
	ds_write_b16 v33, v1 offset:18496
	v_mul_f32_e32 v1, v54, v0
	v_fma_f32 v1, v151, v1, v155
	v_cvt_pk_bf16_f32 v1, v1, s0
	ds_write_b16 v33, v1 offset:18768
	v_mul_f32_e32 v1, v52, v0
	v_fma_f32 v1, v152, v1, v156
	v_cvt_pk_bf16_f32 v1, v1, s0
	ds_write_b16 v33, v1 offset:19040
	v_mul_f32_e32 v1, v50, v0
	v_fmac_f32_e32 v157, v153, v1
	v_cvt_pk_bf16_f32 v1, v157, s0
	ds_write_b16 v33, v1 offset:19312
	v_mul_f32_e32 v1, v49, v0
	s_waitcnt vmcnt(2)
	v_fma_f32 v1, v16, v1, v20
	v_cvt_pk_bf16_f32 v1, v1, s0
	ds_write_b16 v33, v1 offset:19584
	v_mul_f32_e32 v1, v48, v0
	v_fma_f32 v1, v1, v17, v21
	v_cvt_pk_bf16_f32 v1, v1, s0
	ds_write_b16 v33, v1 offset:19856
	v_mul_f32_e32 v1, v47, v0
	v_fma_f32 v1, v1, v18, v22
	v_cvt_pk_bf16_f32 v1, v1, s0
	ds_write_b16 v33, v1 offset:20128
	v_mul_f32_e32 v1, v46, v0
	v_fmac_f32_e32 v23, v1, v19
	v_cvt_pk_bf16_f32 v1, v23, s0
	ds_write_b16 v33, v1 offset:20400
	v_mul_f32_e32 v1, v45, v0
	s_waitcnt vmcnt(0)
	v_fma_f32 v1, v1, v8, v12
	v_cvt_pk_bf16_f32 v1, v1, s0
	ds_write_b16 v33, v1 offset:20672
	v_mul_f32_e32 v1, v44, v0
	v_fma_f32 v1, v1, v9, v13
	v_cvt_pk_bf16_f32 v1, v1, s0
	ds_write_b16 v33, v1 offset:20944
	v_mul_f32_e32 v1, v43, v0
	v_mul_f32_e32 v0, v42, v0
	v_fma_f32 v1, v1, v10, v14
	v_fmac_f32_e32 v15, v0, v11
	v_cvt_pk_bf16_f32 v1, v1, s0
	v_cvt_pk_bf16_f32 v0, v15, s0
	v_ashrrev_i32_e32 v12, 7, v143
	v_lshlrev_b32_e32 v13, 3, v145
	v_mov_b32_e32 v19, 0
	v_add_u32_e32 v20, v38, v144
	ds_write_b16 v33, v1 offset:21216
	ds_write_b16 v33, v0 offset:21488
	v_cmp_lt_i32_e32 vcc, -1, v12
	v_mul_u32_u24_e32 v28, 0x110, v144
	v_lshlrev_b32_e32 v29, 4, v145
	v_lshlrev_b32_e32 v27, 1, v143
	v_add_u32_e32 v25, 1, v12
	v_add_u32_e32 v26, 7, v13
	v_ashrrev_i32_e32 v21, 31, v20
	v_mov_b32_e32 v18, v19
	v_mov_b32_e32 v17, v19
	v_mov_b32_e32 v16, v19
	v_mov_b32_e32 v11, v19
	v_mov_b32_e32 v10, v19
	v_mov_b32_e32 v9, v19
	v_mov_b32_e32 v8, v19
	v_mov_b32_e32 v7, v19
	v_mov_b32_e32 v6, v19
	v_mov_b32_e32 v5, v19
	v_mov_b32_e32 v4, v19
	v_mov_b32_e32 v3, v19
	v_mov_b32_e32 v2, v19
	v_mov_b32_e32 v1, v19
	v_mov_b32_e32 v0, v19
	s_waitcnt lgkmcnt(0)
	s_barrier
	s_and_b32 s2, s12, 3
	s_lshl_b32 s2, s2, 7
	s_add_i32 s20, s11, s2
	s_mov_b32 s21, s81
	v_lshl_add_u64 v[202:203], v[20:21], 0, s[20:21]
	v_lshlrev_b64 v[202:203], 9, v[202:203]
	s_movk_i32 s2, 0x60
	v_and_or_b32 v202, v27, s2, v202
	v_lshl_add_u64 v[202:203], s[30:31], 0, v[202:203]
	global_load_dwordx4 v[204:207], v[202:203], off
	global_load_dwordx4 v[208:211], v[202:203], off offset:-16
	global_load_dwordx4 v[212:215], v[202:203], off offset:128
	global_load_dwordx4 v[216:219], v[202:203], off offset:112
	global_load_dwordx4 v[220:223], v[202:203], off offset:256
	global_load_dwordx4 v[230:233], v[202:203], off offset:240
	global_load_dwordx4 v[234:237], v[202:203], off offset:384
	global_load_dwordx4 v[238:241], v[202:203], off offset:368
	v_lshl_add_u64 v[170:171], v[38:39], 2, s[22:23]
	v_lshlrev_b32_e32 v172, 2, v142
	v_mov_b32_e32 v173, v191
	v_lshl_add_u64 v[170:171], v[170:171], 0, v[172:173]
	s_or_b32 s2, s15, s10
	s_lshl_b32 s20, s2, 7
	s_mov_b32 s21, s81
	v_lshl_add_u64 v[172:173], s[20:21], 2, v[170:171]
	global_load_dwordx4 v[242:245], v[172:173], off
	s_or_b32 s2, s14, s10
	s_lshl_b32 s20, s2, 7
	v_lshl_add_u64 v[172:173], s[20:21], 2, v[170:171]
	global_load_dwordx4 v[246:249], v[172:173], off
	s_and_saveexec_b64 s[34:35], vcc
	s_cbranch_execz .LBB0_550
	s_and_b32 s2, s12, 3
	s_lshl_b32 s2, s2, 7
	s_add_i32 s20, s11, s2
	s_mov_b32 s21, s81
	v_lshl_add_u64 v[0:1], v[20:21], 0, s[20:21]
	v_lshlrev_b64 v[0:1], 9, v[0:1]
	s_movk_i32 s2, 0x60
	v_and_or_b32 v0, v27, s2, v0
	v_add_u32_e32 v14, 1, v12
	v_add_u32_e32 v15, 7, v13
	v_lshl_add_u64 v[12:13], s[30:31], 0, v[0:1]
	v_mov_b32_e32 v0, 0
	v_add3_u32 v22, v28, v29, 0
	s_mov_b64 s[36:37], 0
	v_mov_b32_e32 v1, v0
	v_mov_b32_e32 v2, v0
	v_mov_b32_e32 v3, v0
	v_mov_b32_e32 v4, v0
	v_mov_b32_e32 v5, v0
	v_mov_b32_e32 v6, v0
	v_mov_b32_e32 v7, v0
	v_mov_b32_e32 v8, v0
	v_mov_b32_e32 v9, v0
	v_mov_b32_e32 v10, v0
	v_mov_b32_e32 v11, v0
	v_mov_b32_e32 v16, v0
	v_mov_b32_e32 v17, v0
	v_mov_b32_e32 v18, v0
	v_mov_b32_e32 v19, v0
.LBB0_548:
	s_waitcnt vmcnt(2)
	v_add_u32_e32 v23, -7, v15
	v_cmp_le_i32_e64 s[40:41], v23, v24
	v_add_u32_e32 v31, -5, v15
	v_add_u32_e32 v33, -4, v15
	v_add_u32_e32 v40, -3, v15
	v_cmp_lt_i32_e64 s[42:43], v23, v24
	v_add_u32_e32 v14, -1, v14
	v_lshl_add_u64 v[12:13], v[12:13], 0, s[84:85]
	v_cndmask_b32_e64 v30, 0, v208, s[40:41]
	v_cmp_le_i32_e64 s[40:41], v31, v24
	v_cndmask_b32_e64 v23, 0, v209, s[42:43]
	s_nop 0
	v_cndmask_b32_e64 v31, 0, v210, s[40:41]
	v_cmp_le_i32_e64 s[40:41], v33, v24
	s_nop 1
	v_cndmask_b32_e64 v33, 0, v211, s[40:41]
	v_cmp_le_i32_e64 s[40:41], v40, v24
	s_nop 1
	v_cndmask_b32_e64 v40, 0, v204, s[40:41]
	v_add_u32_e32 v42, -2, v15
	v_cmp_le_i32_e64 s[40:41], v42, v24
	v_add_u32_e32 v42, -1, v15
	s_nop 0
	v_cndmask_b32_e64 v46, 0, v205, s[40:41]
	v_cmp_le_i32_e64 s[40:41], v42, v24
	v_cvt_pk_bf16_f32 v42, v30, v23
	v_cvt_pk_bf16_f32 v43, v31, v33
	v_cndmask_b32_e64 v47, 0, v206, s[40:41]
	v_cmp_le_i32_e64 s[40:41], v15, v24
	v_cvt_pk_bf16_f32 v44, v40, v46
	v_add_u32_e32 v15, 32, v15
	v_cndmask_b32_e64 v45, 0, v207, s[40:41]
	v_cvt_pk_bf16_f32 v45, v47, v45
	ds_read_b128 v[46:49], v22
	v_cmp_eq_u32_e64 s[40:41], 0, v14
	s_waitcnt lgkmcnt(0)
	v_mfma_f32_16x16x32_bf16 v[16:19], v[42:45], v[46:49], v[16:19]
	ds_read_b128 v[46:49], v22 offset:4352
	s_or_b64 s[36:37], s[40:41], s[36:37]
	s_waitcnt lgkmcnt(0)
	v_mfma_f32_16x16x32_bf16 v[8:11], v[42:45], v[46:49], v[8:11]
	ds_read_b128 v[46:49], v22 offset:8704
	s_waitcnt lgkmcnt(0)
	v_mfma_f32_16x16x32_bf16 v[4:7], v[42:45], v[46:49], v[4:7]
	ds_read_b128 v[46:49], v22 offset:13056
	v_add_u32_e32 v22, 64, v22
	s_waitcnt lgkmcnt(0)
	v_mfma_f32_16x16x32_bf16 v[0:3], v[42:45], v[46:49], v[0:3]
	s_andn2_b64 exec, exec, s[36:37]
	s_cbranch_execz .Lgm_a_done
	v_add_u32_e32 v23, -7, v15
	v_cmp_le_i32_e64 s[40:41], v23, v24
	v_add_u32_e32 v31, -5, v15
	v_add_u32_e32 v33, -4, v15
	v_add_u32_e32 v40, -3, v15
	v_cmp_lt_i32_e64 s[42:43], v23, v24
	v_add_u32_e32 v14, -1, v14
	v_lshl_add_u64 v[12:13], v[12:13], 0, s[84:85]
	v_cndmask_b32_e64 v30, 0, v216, s[40:41]
	v_cmp_le_i32_e64 s[40:41], v31, v24
	v_cndmask_b32_e64 v23, 0, v217, s[42:43]
	s_nop 0
	v_cndmask_b32_e64 v31, 0, v218, s[40:41]
	v_cmp_le_i32_e64 s[40:41], v33, v24
	s_nop 1
	v_cndmask_b32_e64 v33, 0, v219, s[40:41]
	v_cmp_le_i32_e64 s[40:41], v40, v24
	s_nop 1
	v_cndmask_b32_e64 v40, 0, v212, s[40:41]
	v_add_u32_e32 v42, -2, v15
	v_cmp_le_i32_e64 s[40:41], v42, v24
	v_add_u32_e32 v42, -1, v15
	s_nop 0
	v_cndmask_b32_e64 v46, 0, v213, s[40:41]
	v_cmp_le_i32_e64 s[40:41], v42, v24
	v_cvt_pk_bf16_f32 v42, v30, v23
	v_cvt_pk_bf16_f32 v43, v31, v33
	v_cndmask_b32_e64 v47, 0, v214, s[40:41]
	v_cmp_le_i32_e64 s[40:41], v15, v24
	v_cvt_pk_bf16_f32 v44, v40, v46
	v_add_u32_e32 v15, 32, v15
	v_cndmask_b32_e64 v45, 0, v215, s[40:41]
	v_cvt_pk_bf16_f32 v45, v47, v45
	ds_read_b128 v[46:49], v22
	v_cmp_eq_u32_e64 s[40:41], 0, v14
	s_waitcnt lgkmcnt(0)
	v_mfma_f32_16x16x32_bf16 v[16:19], v[42:45], v[46:49], v[16:19]
	ds_read_b128 v[46:49], v22 offset:4352
	s_or_b64 s[36:37], s[40:41], s[36:37]
	s_waitcnt lgkmcnt(0)
	v_mfma_f32_16x16x32_bf16 v[8:11], v[42:45], v[46:49], v[8:11]
	ds_read_b128 v[46:49], v22 offset:8704
	s_waitcnt lgkmcnt(0)
	v_mfma_f32_16x16x32_bf16 v[4:7], v[42:45], v[46:49], v[4:7]
	ds_read_b128 v[46:49], v22 offset:13056
	v_add_u32_e32 v22, 64, v22
	s_waitcnt lgkmcnt(0)
	v_mfma_f32_16x16x32_bf16 v[0:3], v[42:45], v[46:49], v[0:3]
	s_andn2_b64 exec, exec, s[36:37]
	s_cbranch_execz .Lgm_a_done
	v_add_u32_e32 v23, -7, v15
	v_cmp_le_i32_e64 s[40:41], v23, v24
	v_add_u32_e32 v31, -5, v15
	v_add_u32_e32 v33, -4, v15
	v_add_u32_e32 v40, -3, v15
	v_cmp_lt_i32_e64 s[42:43], v23, v24
	v_add_u32_e32 v14, -1, v14
	v_lshl_add_u64 v[12:13], v[12:13], 0, s[84:85]
	v_cndmask_b32_e64 v30, 0, v230, s[40:41]
	v_cmp_le_i32_e64 s[40:41], v31, v24
	v_cndmask_b32_e64 v23, 0, v231, s[42:43]
	s_nop 0
	v_cndmask_b32_e64 v31, 0, v232, s[40:41]
	v_cmp_le_i32_e64 s[40:41], v33, v24
	s_nop 1
	v_cndmask_b32_e64 v33, 0, v233, s[40:41]
	v_cmp_le_i32_e64 s[40:41], v40, v24
	s_nop 1
	v_cndmask_b32_e64 v40, 0, v220, s[40:41]
	v_add_u32_e32 v42, -2, v15
	v_cmp_le_i32_e64 s[40:41], v42, v24
	v_add_u32_e32 v42, -1, v15
	s_nop 0
	v_cndmask_b32_e64 v46, 0, v221, s[40:41]
	v_cmp_le_i32_e64 s[40:41], v42, v24
	v_cvt_pk_bf16_f32 v42, v30, v23
	v_cvt_pk_bf16_f32 v43, v31, v33
	v_cndmask_b32_e64 v47, 0, v222, s[40:41]
	v_cmp_le_i32_e64 s[40:41], v15, v24
	v_cvt_pk_bf16_f32 v44, v40, v46
	v_add_u32_e32 v15, 32, v15
	v_cndmask_b32_e64 v45, 0, v223, s[40:41]
	v_cvt_pk_bf16_f32 v45, v47, v45
	ds_read_b128 v[46:49], v22
	v_cmp_eq_u32_e64 s[40:41], 0, v14
	s_waitcnt lgkmcnt(0)
	v_mfma_f32_16x16x32_bf16 v[16:19], v[42:45], v[46:49], v[16:19]
	ds_read_b128 v[46:49], v22 offset:4352
	s_or_b64 s[36:37], s[40:41], s[36:37]
	s_waitcnt lgkmcnt(0)
	v_mfma_f32_16x16x32_bf16 v[8:11], v[42:45], v[46:49], v[8:11]
	ds_read_b128 v[46:49], v22 offset:8704
	s_waitcnt lgkmcnt(0)
	v_mfma_f32_16x16x32_bf16 v[4:7], v[42:45], v[46:49], v[4:7]
	ds_read_b128 v[46:49], v22 offset:13056
	v_add_u32_e32 v22, 64, v22
	s_waitcnt lgkmcnt(0)
	v_mfma_f32_16x16x32_bf16 v[0:3], v[42:45], v[46:49], v[0:3]
	s_andn2_b64 exec, exec, s[36:37]
	s_cbranch_execz .Lgm_a_done
	v_add_u32_e32 v23, -7, v15
	v_cmp_le_i32_e64 s[40:41], v23, v24
	v_add_u32_e32 v31, -5, v15
	v_add_u32_e32 v33, -4, v15
	v_add_u32_e32 v40, -3, v15
	v_cmp_lt_i32_e64 s[42:43], v23, v24
	v_add_u32_e32 v14, -1, v14
	v_lshl_add_u64 v[12:13], v[12:13], 0, s[84:85]
	v_cndmask_b32_e64 v30, 0, v238, s[40:41]
	v_cmp_le_i32_e64 s[40:41], v31, v24
	v_cndmask_b32_e64 v23, 0, v239, s[42:43]
	s_nop 0
	v_cndmask_b32_e64 v31, 0, v240, s[40:41]
	v_cmp_le_i32_e64 s[40:41], v33, v24
	s_nop 1
	v_cndmask_b32_e64 v33, 0, v241, s[40:41]
	v_cmp_le_i32_e64 s[40:41], v40, v24
	s_nop 1
	v_cndmask_b32_e64 v40, 0, v234, s[40:41]
	v_add_u32_e32 v42, -2, v15
	v_cmp_le_i32_e64 s[40:41], v42, v24
	v_add_u32_e32 v42, -1, v15
	s_nop 0
	v_cndmask_b32_e64 v46, 0, v235, s[40:41]
	v_cmp_le_i32_e64 s[40:41], v42, v24
	v_cvt_pk_bf16_f32 v42, v30, v23
	v_cvt_pk_bf16_f32 v43, v31, v33
	v_cndmask_b32_e64 v47, 0, v236, s[40:41]
	v_cmp_le_i32_e64 s[40:41], v15, v24
	v_cvt_pk_bf16_f32 v44, v40, v46
	v_add_u32_e32 v15, 32, v15
	v_cndmask_b32_e64 v45, 0, v237, s[40:41]
	v_cvt_pk_bf16_f32 v45, v47, v45
	ds_read_b128 v[46:49], v22
	v_cmp_eq_u32_e64 s[40:41], 0, v14
	s_waitcnt lgkmcnt(0)
	v_mfma_f32_16x16x32_bf16 v[16:19], v[42:45], v[46:49], v[16:19]
	ds_read_b128 v[46:49], v22 offset:4352
	s_or_b64 s[36:37], s[40:41], s[36:37]
	s_waitcnt lgkmcnt(0)
	v_mfma_f32_16x16x32_bf16 v[8:11], v[42:45], v[46:49], v[8:11]
	ds_read_b128 v[46:49], v22 offset:8704
	s_waitcnt lgkmcnt(0)
	v_mfma_f32_16x16x32_bf16 v[4:7], v[42:45], v[46:49], v[4:7]
	ds_read_b128 v[46:49], v22 offset:13056
	v_add_u32_e32 v22, 64, v22
	s_waitcnt lgkmcnt(0)
	v_mfma_f32_16x16x32_bf16 v[0:3], v[42:45], v[46:49], v[0:3]
	s_andn2_b64 exec, exec, s[36:37]

.LBB0_550:
	s_or_b64 exec, exec, s[34:35]
	s_add_i32 s100, s11, s80
	s_mov_b32 s101, s81
	v_lshl_add_u64 v[202:203], v[20:21], 0, s[100:101]
	v_lshlrev_b64 v[202:203], 9, v[202:203]
	s_movk_i32 s2, 0x60
	v_and_or_b32 v202, v27, s2, v202
	v_lshl_add_u64 v[202:203], s[30:31], 0, v[202:203]
	global_load_dwordx4 v[204:207], v[202:203], off
	global_load_dwordx4 v[208:211], v[202:203], off offset:-16
	global_load_dwordx4 v[212:215], v[202:203], off offset:128
	global_load_dwordx4 v[216:219], v[202:203], off offset:112
	global_load_dwordx4 v[220:223], v[202:203], off offset:256
	global_load_dwordx4 v[230:233], v[202:203], off offset:240
	global_load_dwordx4 v[234:237], v[202:203], off offset:384
	global_load_dwordx4 v[238:241], v[202:203], off offset:368
	v_lshl_add_u64 v[12:13], v[38:39], 2, s[22:23]
	v_lshlrev_b32_e32 v14, 2, v142
	v_mov_b32_e32 v15, v191
	s_or_b32 s2, s15, s10
	v_lshl_add_u64 v[22:23], v[12:13], 0, v[14:15]
	s_lshl_b32 s20, s2, 7
	s_mov_b32 s21, s81
	v_lshl_add_u64 v[12:13], s[20:21], 2, v[22:23]
	v_lshlrev_b32_e32 v33, 16, v141
	v_lshl_add_u64 v[30:31], s[24:25], 0, v[190:191]
	v_lshlrev_b64 v[36:37], 11, v[36:37]
	v_lshl_add_u64 v[38:39], v[30:31], 0, v[36:37]
	v_or_b32_e32 v42, 0x1000, v36
	v_mov_b32_e32 v43, v37
	v_or_b32_e32 v44, 0x1800, v36
	v_mov_b32_e32 v45, v37
	s_waitcnt vmcnt(8)
	v_mov_b32_e32 v12, v242
	v_mov_b32_e32 v13, v243
	v_mov_b32_e32 v14, v244
	v_mov_b32_e32 v15, v245
	v_add_f32_e32 v16, v16, v12
	v_mul_f32_e32 v16, v16, v33
	v_lshlrev_b32_e32 v33, 16, v140
	v_mul_f32_e32 v16, v16, v33
	v_cvt_pk_bf16_f32 v16, v16, s0
	global_store_short v[38:39], v16, off
	v_add_f32_e32 v16, v17, v13
	v_lshlrev_b32_e32 v17, 16, v139
	v_mul_f32_e32 v16, v16, v17
	v_lshlrev_b32_e32 v17, 16, v138
	v_mul_f32_e32 v16, v16, v17
	v_or_b32_e32 v38, 0x800, v36
	v_mov_b32_e32 v39, v37
	v_cvt_pk_bf16_f32 v33, v16, s0
	v_lshl_add_u64 v[16:17], v[30:31], 0, v[38:39]
	global_store_short v[16:17], v33, off
	v_add_f32_e32 v16, v18, v14
	v_lshlrev_b32_e32 v17, 16, v137
	v_mul_f32_e32 v16, v16, v17
	v_lshlrev_b32_e32 v17, 16, v136
	v_mul_f32_e32 v16, v16, v17
	v_cvt_pk_bf16_f32 v18, v16, s0
	v_lshl_add_u64 v[16:17], v[30:31], 0, v[42:43]
	global_store_short v[16:17], v18, off
	v_add_f32_e32 v16, v19, v15
	v_lshlrev_b32_e32 v17, 16, v135
	v_mul_f32_e32 v16, v16, v17
	v_lshlrev_b32_e32 v17, 16, v134
	v_mul_f32_e32 v16, v16, v17
	v_cvt_pk_bf16_f32 v18, v16, s0
	v_lshl_add_u64 v[16:17], v[30:31], 0, v[44:45]
	global_store_short v[16:17], v18, off
	v_add_f32_e32 v8, v8, v12
	v_lshlrev_b32_e32 v16, 16, v133
	v_mul_f32_e32 v8, v8, v16
	v_lshlrev_b32_e32 v16, 16, v132
	v_mul_f32_e32 v8, v8, v16
	v_lshl_add_u64 v[16:17], s[24:25], 0, v[36:37]
	v_or_b32_e32 v30, 32, v190
	v_mov_b32_e32 v31, v191
	v_cvt_pk_bf16_f32 v8, v8, s0
	v_lshl_add_u64 v[18:19], v[16:17], 0, v[30:31]
	global_store_short v[18:19], v8, off
	v_add_f32_e32 v8, v9, v13
	v_lshlrev_b32_e32 v9, 16, v131
	v_mul_f32_e32 v8, v8, v9
	v_lshlrev_b32_e32 v9, 16, v130
	v_mul_f32_e32 v8, v8, v9
	v_cvt_pk_bf16_f32 v33, v8, s0
	v_lshl_add_u64 v[8:9], s[24:25], 0, v[38:39]
	v_lshl_add_u64 v[18:19], v[8:9], 0, v[30:31]
	global_store_short v[18:19], v33, off
	v_add_f32_e32 v10, v10, v14
	v_lshlrev_b32_e32 v18, 16, v129
	v_mul_f32_e32 v10, v10, v18
	v_lshlrev_b32_e32 v18, 16, v128
	v_mul_f32_e32 v10, v10, v18
	v_lshl_add_u64 v[18:19], s[24:25], 0, v[42:43]
	v_cvt_pk_bf16_f32 v10, v10, s0
	v_lshl_add_u64 v[36:37], v[18:19], 0, v[30:31]
	global_store_short v[36:37], v10, off
	v_add_f32_e32 v10, v11, v15
	v_lshlrev_b32_e32 v11, 16, v127
	v_mul_f32_e32 v10, v10, v11
	v_lshlrev_b32_e32 v11, 16, v126
	v_mul_f32_e32 v10, v10, v11
	v_cvt_pk_bf16_f32 v33, v10, s0
	v_lshl_add_u64 v[10:11], s[24:25], 0, v[44:45]
	v_lshl_add_u64 v[30:31], v[10:11], 0, v[30:31]
	global_store_short v[30:31], v33, off
	v_add_f32_e32 v4, v4, v12
	v_lshlrev_b32_e32 v30, 16, v120
	v_mul_f32_e32 v4, v4, v30
	v_lshlrev_b32_e32 v30, 16, v119
	v_mul_f32_e32 v4, v4, v30
	v_or_b32_e32 v30, 64, v190
	v_mov_b32_e32 v31, v191
	v_cvt_pk_bf16_f32 v4, v4, s0
	v_lshl_add_u64 v[36:37], v[16:17], 0, v[30:31]
	global_store_short v[36:37], v4, off
	v_add_f32_e32 v4, v5, v13
	v_lshlrev_b32_e32 v5, 16, v117
	v_mul_f32_e32 v4, v4, v5
	v_lshlrev_b32_e32 v5, 16, v116
	v_mul_f32_e32 v4, v4, v5
	v_cvt_pk_bf16_f32 v33, v4, s0
	v_lshl_add_u64 v[4:5], v[8:9], 0, v[30:31]
	global_store_short v[4:5], v33, off
	v_add_f32_e32 v4, v6, v14
	v_lshlrev_b32_e32 v5, 16, v114
	v_mul_f32_e32 v4, v4, v5
	v_lshlrev_b32_e32 v5, 16, v113
	v_mul_f32_e32 v4, v4, v5
	v_cvt_pk_bf16_f32 v6, v4, s0
	v_lshl_add_u64 v[4:5], v[18:19], 0, v[30:31]
	global_store_short v[4:5], v6, off
	v_add_f32_e32 v4, v7, v15
	v_lshlrev_b32_e32 v5, 16, v112
	v_mul_f32_e32 v4, v4, v5
	v_lshlrev_b32_e32 v5, 16, v111
	v_mul_f32_e32 v4, v4, v5
	v_cvt_pk_bf16_f32 v6, v4, s0
	v_lshl_add_u64 v[4:5], v[10:11], 0, v[30:31]
	global_store_short v[4:5], v6, off
	v_add_f32_e32 v0, v0, v12
	v_lshlrev_b32_e32 v4, 16, v110
	v_mul_f32_e32 v0, v0, v4
	v_lshlrev_b32_e32 v4, 16, v118
	v_mul_f32_e32 v0, v0, v4
	v_or_b32_e32 v190, 0x60, v190
	v_cvt_pk_bf16_f32 v0, v0, s0
	v_lshl_add_u64 v[4:5], v[16:17], 0, v[190:191]
	global_store_short v[4:5], v0, off
	v_add_f32_e32 v0, v1, v13
	v_lshlrev_b32_e32 v1, 16, v115
	v_mul_f32_e32 v0, v0, v1
	v_lshlrev_b32_e32 v1, 16, v122
	v_mul_f32_e32 v0, v0, v1
	v_cvt_pk_bf16_f32 v4, v0, s0
	v_lshl_add_u64 v[0:1], v[8:9], 0, v[190:191]
	global_store_short v[0:1], v4, off
	v_add_f32_e32 v0, v2, v14
	v_lshlrev_b32_e32 v1, 16, v121
	v_mul_f32_e32 v0, v0, v1
	v_lshlrev_b32_e32 v1, 16, v124
	v_mul_f32_e32 v0, v0, v1
	v_cvt_pk_bf16_f32 v2, v0, s0
	v_lshl_add_u64 v[0:1], v[18:19], 0, v[190:191]
	global_store_short v[0:1], v2, off
	v_add_f32_e32 v0, v3, v15
	v_lshlrev_b32_e32 v1, 16, v123
	v_mul_f32_e32 v0, v0, v1
	v_lshlrev_b32_e32 v1, 16, v125
	v_mul_f32_e32 v0, v0, v1
	v_cvt_pk_bf16_f32 v2, v0, s0
	v_lshl_add_u64 v[0:1], v[10:11], 0, v[190:191]
	v_mov_b32_e32 v19, 0
	global_store_short v[0:1], v2, off
	v_mov_b32_e32 v18, v19
	v_mov_b32_e32 v17, v19
	v_mov_b32_e32 v16, v19
	v_mov_b32_e32 v11, v19
	v_mov_b32_e32 v10, v19
	v_mov_b32_e32 v9, v19
	v_mov_b32_e32 v8, v19
	v_mov_b32_e32 v7, v19
	v_mov_b32_e32 v6, v19
	v_mov_b32_e32 v5, v19
	v_mov_b32_e32 v4, v19
	v_mov_b32_e32 v3, v19
	v_mov_b32_e32 v2, v19
	v_mov_b32_e32 v1, v19
	v_mov_b32_e32 v0, v19
	s_and_saveexec_b64 s[34:35], vcc
	s_cbranch_execz .LBB0_545
	s_add_i32 s80, s11, s80
	v_readlane_b32 s2, v252, 15
	v_lshl_add_u64 v[0:1], v[20:21], 0, s[80:81]
	v_lshlrev_b64 v[0:1], 9, v[0:1]
	v_add3_u32 v14, v28, v29, s2
	s_movk_i32 s2, 0x60
	v_and_or_b32 v0, v27, s2, v0
	v_lshl_add_u64 v[12:13], s[30:31], 0, v[0:1]
	v_mov_b32_e32 v0, 0
	s_mov_b64 s[36:37], 0
	v_mov_b32_e32 v1, v0
	v_mov_b32_e32 v2, v0
	v_mov_b32_e32 v3, v0
	v_mov_b32_e32 v4, v0
	v_mov_b32_e32 v5, v0
	v_mov_b32_e32 v6, v0
	v_mov_b32_e32 v7, v0
	v_mov_b32_e32 v8, v0
	v_mov_b32_e32 v9, v0
	v_mov_b32_e32 v10, v0
	v_mov_b32_e32 v11, v0
	v_mov_b32_e32 v16, v0
	v_mov_b32_e32 v17, v0
	v_mov_b32_e32 v18, v0
	v_mov_b32_e32 v19, v0
.LBB0_552:
	s_waitcnt vmcnt(16)
	v_add_u32_e32 v15, -7, v26
	v_cmp_le_i32_e32 vcc, v15, v24
	v_add_u32_e32 v21, -5, v26
	v_add_u32_e32 v27, -4, v26
	v_add_u32_e32 v33, -3, v26
	v_cmp_lt_i32_e64 s[40:41], v15, v24
	v_add_u32_e32 v25, -1, v25
	v_lshl_add_u64 v[12:13], v[12:13], 0, s[84:85]
	v_cndmask_b32_e32 v20, 0, v208, vcc
	v_cmp_le_i32_e32 vcc, v21, v24
	v_cndmask_b32_e64 v15, 0, v209, s[40:41]
	s_nop 0
	v_cndmask_b32_e32 v21, 0, v210, vcc
	v_cmp_le_i32_e32 vcc, v27, v24
	s_nop 1
	v_cndmask_b32_e32 v27, 0, v211, vcc
	v_cmp_le_i32_e32 vcc, v33, v24
	s_nop 1
	v_cndmask_b32_e32 v33, 0, v204, vcc
	v_add_u32_e32 v28, -2, v26
	v_cmp_le_i32_e32 vcc, v28, v24
	v_add_u32_e32 v28, -1, v26
	s_nop 0
	v_cndmask_b32_e32 v36, 0, v205, vcc
	v_cmp_le_i32_e32 vcc, v28, v24
	v_cvt_pk_bf16_f32 v28, v20, v15
	v_cvt_pk_bf16_f32 v29, v21, v27
	v_cndmask_b32_e32 v37, 0, v206, vcc
	v_cmp_le_i32_e32 vcc, v26, v24
	v_cvt_pk_bf16_f32 v30, v33, v36
	v_add_u32_e32 v26, 32, v26
	v_cndmask_b32_e32 v31, 0, v207, vcc
	v_cvt_pk_bf16_f32 v31, v37, v31
	ds_read_b128 v[36:39], v14
	v_cmp_eq_u32_e32 vcc, 0, v25
	s_waitcnt lgkmcnt(0)
	v_mfma_f32_16x16x32_bf16 v[16:19], v[28:31], v[36:39], v[16:19]
	ds_read_b128 v[36:39], v14 offset:4352
	s_or_b64 s[36:37], vcc, s[36:37]
	s_waitcnt lgkmcnt(0)
	v_mfma_f32_16x16x32_bf16 v[8:11], v[28:31], v[36:39], v[8:11]
	ds_read_b128 v[36:39], v14 offset:8704
	s_waitcnt lgkmcnt(0)
	v_mfma_f32_16x16x32_bf16 v[4:7], v[28:31], v[36:39], v[4:7]
	ds_read_b128 v[36:39], v14 offset:13056
	v_add_u32_e32 v14, 64, v14
	s_waitcnt lgkmcnt(0)
	v_mfma_f32_16x16x32_bf16 v[0:3], v[28:31], v[36:39], v[0:3]
	s_andn2_b64 exec, exec, s[36:37]
	s_cbranch_execz .Lgm_b_done
	v_add_u32_e32 v15, -7, v26
	v_cmp_le_i32_e32 vcc, v15, v24
	v_add_u32_e32 v21, -5, v26
	v_add_u32_e32 v27, -4, v26
	v_add_u32_e32 v33, -3, v26
	v_cmp_lt_i32_e64 s[40:41], v15, v24
	v_add_u32_e32 v25, -1, v25
	v_lshl_add_u64 v[12:13], v[12:13], 0, s[84:85]
	v_cndmask_b32_e32 v20, 0, v216, vcc
	v_cmp_le_i32_e32 vcc, v21, v24
	v_cndmask_b32_e64 v15, 0, v217, s[40:41]
	s_nop 0
	v_cndmask_b32_e32 v21, 0, v218, vcc
	v_cmp_le_i32_e32 vcc, v27, v24
	s_nop 1
	v_cndmask_b32_e32 v27, 0, v219, vcc
	v_cmp_le_i32_e32 vcc, v33, v24
	s_nop 1
	v_cndmask_b32_e32 v33, 0, v212, vcc
	v_add_u32_e32 v28, -2, v26
	v_cmp_le_i32_e32 vcc, v28, v24
	v_add_u32_e32 v28, -1, v26
	s_nop 0
	v_cndmask_b32_e32 v36, 0, v213, vcc
	v_cmp_le_i32_e32 vcc, v28, v24
	v_cvt_pk_bf16_f32 v28, v20, v15
	v_cvt_pk_bf16_f32 v29, v21, v27
	v_cndmask_b32_e32 v37, 0, v214, vcc
	v_cmp_le_i32_e32 vcc, v26, v24
	v_cvt_pk_bf16_f32 v30, v33, v36
	v_add_u32_e32 v26, 32, v26
	v_cndmask_b32_e32 v31, 0, v215, vcc
	v_cvt_pk_bf16_f32 v31, v37, v31
	ds_read_b128 v[36:39], v14
	v_cmp_eq_u32_e32 vcc, 0, v25
	s_waitcnt lgkmcnt(0)
	v_mfma_f32_16x16x32_bf16 v[16:19], v[28:31], v[36:39], v[16:19]
	ds_read_b128 v[36:39], v14 offset:4352
	s_or_b64 s[36:37], vcc, s[36:37]
	s_waitcnt lgkmcnt(0)
	v_mfma_f32_16x16x32_bf16 v[8:11], v[28:31], v[36:39], v[8:11]
	ds_read_b128 v[36:39], v14 offset:8704
	s_waitcnt lgkmcnt(0)
	v_mfma_f32_16x16x32_bf16 v[4:7], v[28:31], v[36:39], v[4:7]
	ds_read_b128 v[36:39], v14 offset:13056
	v_add_u32_e32 v14, 64, v14
	s_waitcnt lgkmcnt(0)
	v_mfma_f32_16x16x32_bf16 v[0:3], v[28:31], v[36:39], v[0:3]
	s_andn2_b64 exec, exec, s[36:37]
	s_cbranch_execz .Lgm_b_done
	v_add_u32_e32 v15, -7, v26
	v_cmp_le_i32_e32 vcc, v15, v24
	v_add_u32_e32 v21, -5, v26
	v_add_u32_e32 v27, -4, v26
	v_add_u32_e32 v33, -3, v26
	v_cmp_lt_i32_e64 s[40:41], v15, v24
	v_add_u32_e32 v25, -1, v25
	v_lshl_add_u64 v[12:13], v[12:13], 0, s[84:85]
	v_cndmask_b32_e32 v20, 0, v230, vcc
	v_cmp_le_i32_e32 vcc, v21, v24
	v_cndmask_b32_e64 v15, 0, v231, s[40:41]
	s_nop 0
	v_cndmask_b32_e32 v21, 0, v232, vcc
	v_cmp_le_i32_e32 vcc, v27, v24
	s_nop 1
	v_cndmask_b32_e32 v27, 0, v233, vcc
	v_cmp_le_i32_e32 vcc, v33, v24
	s_nop 1
	v_cndmask_b32_e32 v33, 0, v220, vcc
	v_add_u32_e32 v28, -2, v26
	v_cmp_le_i32_e32 vcc, v28, v24
	v_add_u32_e32 v28, -1, v26
	s_nop 0
	v_cndmask_b32_e32 v36, 0, v221, vcc
	v_cmp_le_i32_e32 vcc, v28, v24
	v_cvt_pk_bf16_f32 v28, v20, v15
	v_cvt_pk_bf16_f32 v29, v21, v27
	v_cndmask_b32_e32 v37, 0, v222, vcc
	v_cmp_le_i32_e32 vcc, v26, v24
	v_cvt_pk_bf16_f32 v30, v33, v36
	v_add_u32_e32 v26, 32, v26
	v_cndmask_b32_e32 v31, 0, v223, vcc
	v_cvt_pk_bf16_f32 v31, v37, v31
	ds_read_b128 v[36:39], v14
	v_cmp_eq_u32_e32 vcc, 0, v25
	s_waitcnt lgkmcnt(0)
	v_mfma_f32_16x16x32_bf16 v[16:19], v[28:31], v[36:39], v[16:19]
	ds_read_b128 v[36:39], v14 offset:4352
	s_or_b64 s[36:37], vcc, s[36:37]
	s_waitcnt lgkmcnt(0)
	v_mfma_f32_16x16x32_bf16 v[8:11], v[28:31], v[36:39], v[8:11]
	ds_read_b128 v[36:39], v14 offset:8704
	s_waitcnt lgkmcnt(0)
	v_mfma_f32_16x16x32_bf16 v[4:7], v[28:31], v[36:39], v[4:7]
	ds_read_b128 v[36:39], v14 offset:13056
	v_add_u32_e32 v14, 64, v14
	s_waitcnt lgkmcnt(0)
	v_mfma_f32_16x16x32_bf16 v[0:3], v[28:31], v[36:39], v[0:3]
	s_andn2_b64 exec, exec, s[36:37]
	s_cbranch_execz .Lgm_b_done
	v_add_u32_e32 v15, -7, v26
	v_cmp_le_i32_e32 vcc, v15, v24
	v_add_u32_e32 v21, -5, v26
	v_add_u32_e32 v27, -4, v26
	v_add_u32_e32 v33, -3, v26
	v_cmp_lt_i32_e64 s[40:41], v15, v24
	v_add_u32_e32 v25, -1, v25
	v_lshl_add_u64 v[12:13], v[12:13], 0, s[84:85]
	v_cndmask_b32_e32 v20, 0, v238, vcc
	v_cmp_le_i32_e32 vcc, v21, v24
	v_cndmask_b32_e64 v15, 0, v239, s[40:41]
	s_nop 0
	v_cndmask_b32_e32 v21, 0, v240, vcc
	v_cmp_le_i32_e32 vcc, v27, v24
	s_nop 1
	v_cndmask_b32_e32 v27, 0, v241, vcc
	v_cmp_le_i32_e32 vcc, v33, v24
	s_nop 1
	v_cndmask_b32_e32 v33, 0, v234, vcc
	v_add_u32_e32 v28, -2, v26
	v_cmp_le_i32_e32 vcc, v28, v24
	v_add_u32_e32 v28, -1, v26
	s_nop 0
	v_cndmask_b32_e32 v36, 0, v235, vcc
	v_cmp_le_i32_e32 vcc, v28, v24
	v_cvt_pk_bf16_f32 v28, v20, v15
	v_cvt_pk_bf16_f32 v29, v21, v27
	v_cndmask_b32_e32 v37, 0, v236, vcc
	v_cmp_le_i32_e32 vcc, v26, v24
	v_cvt_pk_bf16_f32 v30, v33, v36
	v_add_u32_e32 v26, 32, v26
	v_cndmask_b32_e32 v31, 0, v237, vcc
	v_cvt_pk_bf16_f32 v31, v37, v31
	ds_read_b128 v[36:39], v14
	v_cmp_eq_u32_e32 vcc, 0, v25
	s_waitcnt lgkmcnt(0)
	v_mfma_f32_16x16x32_bf16 v[16:19], v[28:31], v[36:39], v[16:19]
	ds_read_b128 v[36:39], v14 offset:4352
	s_or_b64 s[36:37], vcc, s[36:37]
	s_waitcnt lgkmcnt(0)
	v_mfma_f32_16x16x32_bf16 v[8:11], v[28:31], v[36:39], v[8:11]
	ds_read_b128 v[36:39], v14 offset:8704
	s_waitcnt lgkmcnt(0)
	v_mfma_f32_16x16x32_bf16 v[4:7], v[28:31], v[36:39], v[4:7]
	ds_read_b128 v[36:39], v14 offset:13056
	v_add_u32_e32 v14, 64, v14
	s_waitcnt lgkmcnt(0)
	v_mfma_f32_16x16x32_bf16 v[0:3], v[28:31], v[36:39], v[0:3]
	s_andn2_b64 exec, exec, s[36:37]
.Lgm_b_done:
	s_or_b64 exec, exec, s[36:37]
	s_branch .LBB0_545
